# q/k RMS-norm + gain for all 24 heads now applied in the in-proj GEMM epilogue; both attention loops stage K and use Q without per-unit norm math
# speedup vs baseline: 1.0254x; 1.0057x over previous
;     __device__ __forceinline__ void operator()(const pg8::f32x4 (&acc)[2][2][4][2], const pg8::Unit& u, int wr, int wc, int fr, int fq) const {
;     ...
;         if (qkv) { const int which = (pn - 4) / 6, ct = (pn - 4) % 6; dsh = 2 * (ct >> 1);
;             base = Q + (size_t)which * ((WS_K - WS_Q) / 2) + (size_t)(ct * 4 + wc) * SEQ * 64; ecol = 32 * hi8 + 8 * fq; }
.LBB0_154:
	s_mov_b32 s100, 0
	s_add_i32 s101, s4, -4
	s_cmp_lt_u32 s101, 12
	s_cbranch_scc0 .Lp1_gdone
	s_cmp_lt_u32 s101, 6
	s_cselect_b32 vcc_lo, s42, s44
	s_cselect_b32 vcc_hi, s43, s45
	s_cselect_b32 s100, 0, 6
	s_sub_i32 s101, s101, s100
	s_cmp_eq_u32 s100, 0
	s_cselect_b32 s100, 0x3e38aa3b, 1.0
	s_cmp_lt_u32 s101, 0
	s_cbranch_scc1 .Lp1_gskip
	s_lshl_b32 s101, s101, 10
	s_add_u32 vcc_lo, vcc_lo, s101
	s_addc_u32 vcc_hi, vcc_hi, 0
	s_mov_b32 s101, s100
	s_mov_b32 s100, 1
	global_load_dwordx4 v[234:237], v250, vcc
	global_load_dwordx4 v[238:241], v250, vcc offset:16
	global_load_dwordx4 v[242:245], v250, vcc offset:128
	global_load_dwordx4 v[246:249], v250, vcc offset:144
	s_branch .Lp1_gdone

; template <bool FUSED> __device__ __forceinline__ void attn_phase(const Args& a, LAS unsigned char* lds, int tid, int lane, int wave) {
;     ...
;         {
;             const int ch = tid & 7;
;             const f32x4 g0 = *(const f32x4*)(a.kw + hd * 64 + ch * 8), g1 = *(const f32x4*)(a.kw + hd * 64 + ch * 8 + 4);
; #pragma unroll
;             for (int i = 0; i < 6; ++i) { const int row = (tid + 512 * i) >> 3;
;                 const float e0 = bflo(kv[i].x), e1 = bfhi(kv[i].x), e2 = bflo(kv[i].y), e3 = bfhi(kv[i].y), e4 = bflo(kv[i].z), e5 = bfhi(kv[i].z), e6 = bflo(kv[i].w), e7 = bfhi(kv[i].w);
;                 float ss = (e0 * e0 + e1 * e1) + (e2 * e2 + e3 * e3) + (e4 * e4 + e5 * e5) + (e6 * e6 + e7 * e7);
;                 ss += dpp_movf<0xB1>(ss); ss += dpp_movf<0x4E>(ss); ss += dpp_movf<0x141>(ss);
;                 const float rk = __builtin_amdgcn_rsqf(ss * (1.f / 64.f) + 1e-6f);
;                 u32x4 wv; wv.x = pk2(e0 * rk * g0.x, e1 * rk * g0.y); wv.y = pk2(e2 * rk * g0.z, e3 * rk * g0.w); wv.z = pk2(e4 * rk * g1.x, e5 * rk * g1.y); wv.w = pk2(e6 * rk * g1.z, e7 * rk * g1.w);
;                 *(LAS u32x4*)(lds + row * KP + ch * 16) = wv;
;                 *(LAS u32x4*)(lds + LDS_VOFF + row * VP + ch * 16) = vv[i];
;                 if (i & 1) __builtin_amdgcn_sched_barrier(0); }
;         }
;         bf16x8 qf[4];
;         {
;             float ss = 0.f;
; #pragma unroll
;             for (int ks = 0; ks < 4; ++ks)
; #pragma unroll
;                 for (int e = 0; e < 4; ++e) { const float lo = bflo(qv[ks][e]), hi = bfhi(qv[ks][e]); ss += lo * lo + hi * hi; }
;             ss += __shfl_xor(ss, 32);
;             const float rq = 0.125f * LOG2E * __builtin_amdgcn_rsqf(ss * (1.f / 64.f) + 1e-6f);
; #pragma unroll
;             for (int ks = 0; ks < 4; ++ks) { const f32x4 g0 = *(const f32x4*)(a.qw + hd * 64 + 16 * ks + 8 * h), g1 = *(const f32x4*)(a.qw + hd * 64 + 16 * ks + 8 * h + 4); u32x4 wv;
;                 wv.x = pk2(bflo(qv[ks].x) * rq * g0.x, bfhi(qv[ks].x) * rq * g0.y); wv.y = pk2(bflo(qv[ks].y) * rq * g0.z, bfhi(qv[ks].y) * rq * g0.w);
;                 wv.z = pk2(bflo(qv[ks].z) * rq * g1.x, bfhi(qv[ks].z) * rq * g1.y); wv.w = pk2(bflo(qv[ks].w) * rq * g1.z, bfhi(qv[ks].w) * rq * g1.w);
;                 qf[ks] = __builtin_bit_cast(bf16x8, wv); }
;         }
;         const float mb = ((const float*)(a.ws + WS_RS))[hd];
.LBB0_402:
	s_ashr_i32 s6, s46, 5
	s_lshr_b32 s7, s6, 29
	s_add_i32 s7, s6, s7
	s_and_b32 s7, s7, -8
	s_sub_i32 s6, s6, s7
	s_ashr_i32 s7, s6, 31
	s_lshl_b64 s[8:9], s[6:7], 2
	s_add_u32 s8, s87, s8
	s_addc_u32 s9, s88, s9
	global_load_dword v229, v147, s[8:9]
	s_waitcnt vmcnt(15)
	ds_write_b128 v194, v[64:67]
	ds_write_b128 v195, v[68:71] offset:55296
	s_waitcnt vmcnt(13)
	ds_write_b128 v196, v[72:75]
	ds_write_b128 v197, v[76:79] offset:55296
	s_waitcnt vmcnt(11)
	ds_write_b128 v198, v[80:83]
	ds_write_b128 v199, v[84:87] offset:55296
	s_waitcnt vmcnt(9)
	ds_write_b128 v200, v[88:91]
	ds_write_b128 v201, v[92:95] offset:55296
	s_waitcnt vmcnt(7)
	ds_write_b128 v202, v[112:115]
	ds_write_b128 v203, v[116:119] offset:55296
	s_waitcnt vmcnt(5)
	ds_write_b128 v204, v[120:123]
	ds_write_b128 v205, v[124:127] offset:55296
	s_add_i32 s64, s46, s54
	s_cmpk_lt_i32 s64, 0x800
	s_cselect_b64 s[44:45], -1, 0
	s_cmpk_gt_i32 s64, 0x7ff
	s_cselect_b64 s[42:43], -1, 0
	s_and_b64 vcc, exec, s[42:43]
	s_waitcnt vmcnt(1)
	v_mov_b32_e32 v136, v96
	v_mov_b32_e32 v137, v97
	v_mov_b32_e32 v138, v98
	v_mov_b32_e32 v139, v99
	v_mov_b32_e32 v132, v100
	v_mov_b32_e32 v133, v101
	v_mov_b32_e32 v134, v102
	v_mov_b32_e32 v135, v103
	v_mov_b32_e32 v128, v104
	v_mov_b32_e32 v129, v105
	v_mov_b32_e32 v130, v106
	v_mov_b32_e32 v131, v107
	v_mov_b32_e32 v140, v108
	v_mov_b32_e32 v141, v109
	v_mov_b32_e32 v142, v110
	v_mov_b32_e32 v143, v111
	s_waitcnt lgkmcnt(0)
	s_barrier
	s_cbranch_vccnz .LBB0_404
	s_ashr_i32 s8, s64, 5
	s_lshr_b32 s9, s8, 29
	s_add_i32 s9, s8, s9
	s_and_b32 s9, s9, -8
	s_sub_i32 s8, s8, s9
	s_ashr_i32 s10, s8, 2
	s_and_b32 s10, s10, -2
	s_lshr_b32 s11, 32, s10
	s_and_b32 s7, s64, 31
	s_lshr_b32 s12, 0x2000, s10
	s_sub_i32 s10, 5, s10
	s_add_i32 s11, s11, -1
	s_lshr_b32 s10, s7, s10
	s_and_b32 s7, s11, s7
	s_lshl_b32 s7, s7, 8
	v_add_u32_e32 v40, s7, v153
	s_add_i32 s11, s12, -1
	v_min_i32_e32 v43, s11, v40
	v_cmp_lt_i32_e32 vcc, -1, v40
	s_mul_i32 s10, s10, s12
	s_ashr_i32 s9, s64, 31
	v_cndmask_b32_e32 v40, 0, v43, vcc
	v_add_u32_e32 v64, s10, v40
	v_add_u32_e32 v40, s7, v155
	v_min_i32_e32 v43, s11, v40
	v_cmp_lt_i32_e32 vcc, -1, v40
	s_lshr_b32 s9, s9, 24
	s_add_i32 s9, s64, s9
	v_cndmask_b32_e32 v40, 0, v43, vcc
	v_add_u32_e32 v72, s10, v40
	v_add_u32_e32 v40, s7, v159
	v_min_i32_e32 v43, s11, v40
	v_cmp_lt_i32_e32 vcc, -1, v40
	s_ashr_i32 s9, s9, 8
	s_mul_i32 s9, s9, 24
	v_cndmask_b32_e32 v40, 0, v43, vcc
	v_add_u32_e32 v80, s10, v40
	v_add_u32_e32 v40, s7, v161
	v_min_i32_e32 v43, s11, v40
	v_cmp_lt_i32_e32 vcc, -1, v40
	s_add_i32 s8, s9, s8
	s_ashr_i32 s9, s8, 31
	v_cndmask_b32_e32 v40, 0, v43, vcc
	v_add_u32_e32 v88, s10, v40
	v_add_u32_e32 v40, s7, v163
	v_min_i32_e32 v43, s11, v40
	v_cmp_lt_i32_e32 vcc, -1, v40
	v_ashrrev_i32_e32 v65, 31, v64
	v_ashrrev_i32_e32 v73, 31, v72
	v_cndmask_b32_e32 v40, 0, v43, vcc
	v_add_u32_e32 v112, s10, v40
	v_add_u32_e32 v40, s7, v176
	v_min_i32_e32 v43, s11, v40
	v_cmp_lt_i32_e32 vcc, -1, v40
	v_ashrrev_i32_e32 v81, 31, v80
	v_ashrrev_i32_e32 v89, 31, v88
	v_cndmask_b32_e32 v40, 0, v43, vcc
	v_add_u32_e32 v120, s10, v40
	v_ashrrev_i32_e32 v113, 31, v112
	v_ashrrev_i32_e32 v121, 31, v120
	s_lshl_b64 s[8:9], s[8:9], 19
	v_lshlrev_b64 v[64:65], 6, v[64:65]
	v_lshlrev_b64 v[72:73], 6, v[72:73]
	v_lshlrev_b64 v[80:81], 6, v[80:81]
	v_lshlrev_b64 v[88:89], 6, v[88:89]
	v_lshlrev_b64 v[112:113], 6, v[112:113]
	v_lshlrev_b64 v[120:121], 6, v[120:121]
	v_lshl_add_u64 v[64:65], v[64:65], 0, s[8:9]
	v_lshl_add_u64 v[72:73], v[72:73], 0, s[8:9]
	v_lshl_add_u64 v[80:81], v[80:81], 0, s[8:9]
	v_lshl_add_u64 v[88:89], v[88:89], 0, s[8:9]
	v_lshl_add_u64 v[112:113], v[112:113], 0, s[8:9]
	v_lshl_add_u64 v[120:121], v[120:121], 0, s[8:9]
	v_or_b32_e32 v64, v64, v144
	v_or_b32_e32 v72, v72, v144
	v_or_b32_e32 v80, v80, v144
	v_or_b32_e32 v88, v88, v144
	v_or_b32_e32 v112, v112, v144
	v_or_b32_e32 v120, v120, v144
	v_lshlrev_b64 v[64:65], 1, v[64:65]
	v_lshlrev_b64 v[72:73], 1, v[72:73]
	v_lshlrev_b64 v[80:81], 1, v[80:81]
	v_lshlrev_b64 v[88:89], 1, v[88:89]
	v_lshlrev_b64 v[112:113], 1, v[112:113]
	v_lshlrev_b64 v[120:121], 1, v[120:121]
	v_lshl_add_u64 v[66:67], s[58:59], 0, v[64:65]
	v_lshl_add_u64 v[68:69], s[60:61], 0, v[64:65]
	v_lshl_add_u64 v[74:75], s[58:59], 0, v[72:73]
	v_lshl_add_u64 v[76:77], s[60:61], 0, v[72:73]
	v_lshl_add_u64 v[82:83], s[58:59], 0, v[80:81]
	v_lshl_add_u64 v[84:85], s[60:61], 0, v[80:81]
	v_lshl_add_u64 v[90:91], s[58:59], 0, v[88:89]
	v_lshl_add_u64 v[92:93], s[60:61], 0, v[88:89]
	v_lshl_add_u64 v[114:115], s[58:59], 0, v[112:113]
	v_lshl_add_u64 v[116:117], s[60:61], 0, v[112:113]
	v_lshl_add_u64 v[122:123], s[58:59], 0, v[120:121]
	v_lshl_add_u64 v[124:125], s[60:61], 0, v[120:121]
	global_load_dwordx4 v[64:67], v[66:67], off
	s_nop 0
	global_load_dwordx4 v[68:71], v[68:69], off
	s_nop 0
	global_load_dwordx4 v[72:75], v[74:75], off
	s_nop 0
	global_load_dwordx4 v[76:79], v[76:77], off
	s_nop 0
	global_load_dwordx4 v[80:83], v[82:83], off
	s_nop 0
	global_load_dwordx4 v[84:87], v[84:85], off
	s_nop 0
	global_load_dwordx4 v[88:91], v[90:91], off
	s_nop 0
	global_load_dwordx4 v[92:95], v[92:93], off
	s_nop 0
	global_load_dwordx4 v[112:115], v[114:115], off
	s_nop 0
	global_load_dwordx4 v[116:119], v[116:117], off
	s_nop 0
	global_load_dwordx4 v[120:123], v[122:123], off
	s_nop 0
	global_load_dwordx4 v[124:127], v[124:125], off
	v_mov_b32_e32 v28, v177
	ds_read_b128 v[24:27], v206 offset:32
	s_and_b32 s65, s6, 7
	ds_read_b128 v[20:23], v206
	s_ashr_i32 s7, s6, 2
	s_add_i32 s6, s65, 1
	s_and_b32 s7, s7, -2
	s_lshr_b32 s8, 32, s7
	s_add_i32 s8, s8, -1
	s_and_b32 s8, s46, s8
	s_waitcnt vmcnt(12)
	s_branch .Lattn2_join
; template <bool FUSED> __device__ __forceinline__ void attn_phase(const Args& a, LAS unsigned char* lds, int tid, int lane, int wave) {
;     ...
;         bf16x8 qf[4];
;         {
;             float ss = 0.f;
; #pragma unroll
;             for (int ks = 0; ks < 4; ++ks)
; #pragma unroll
;                 for (int e = 0; e < 4; ++e) { const float lo = bflo(qv[ks][e]), hi = bfhi(qv[ks][e]); ss += lo * lo + hi * hi; }
;             ss += __shfl_xor(ss, 32);
;             const float rq = 0.125f * LOG2E * __builtin_amdgcn_rsqf(ss * (1.f / 64.f) + 1e-6f);
; #pragma unroll
;             for (int ks = 0; ks < 4; ++ks) { const f32x4 g0 = *(const f32x4*)(a.qw + hd * 64 + 16 * ks + 8 * h), g1 = *(const f32x4*)(a.qw + hd * 64 + 16 * ks + 8 * h + 4); u32x4 wv;
;                 wv.x = pk2(bflo(qv[ks].x) * rq * g0.x, bfhi(qv[ks].x) * rq * g0.y); wv.y = pk2(bflo(qv[ks].y) * rq * g0.z, bfhi(qv[ks].y) * rq * g0.w);
;                 wv.z = pk2(bflo(qv[ks].z) * rq * g1.x, bfhi(qv[ks].z) * rq * g1.y); wv.w = pk2(bflo(qv[ks].w) * rq * g1.z, bfhi(qv[ks].w) * rq * g1.w);
;                 qf[ks] = __builtin_bit_cast(bf16x8, wv); }
;         }
;     ...
;         f32x16 o[2]; o[0] = f32x16{}; o[1] = f32x16{};
; #pragma unroll
;         for (int j = 0; j < 5; ++j) {
;             f32x16 st;
; #pragma unroll
;             for (int i = 0; i < 16; ++i) st[i] = -mb;
;             LAS const unsigned char* kp = lds + (32 * wave + 32 * j + l31) * KP + 16 * h;
; #pragma unroll
;             for (int ks = 0; ks < 4; ++ks) { const bf16x8 kf = *(LAS const bf16x8*)(kp + 32 * ks); st = __builtin_amdgcn_mfma_f32_32x32x16_bf16(kf, qf[ks], st, 0, 0, 0); }
;             sum += attn_tile_exp(st, j, tlf, bsl, rlo, rhi);
; #pragma unroll
;             for (int s2 = 0; s2 < 2; ++s2) { u32x4 pw; pw.x = pk2(st[8 * s2 + 0], st[8 * s2 + 1]); pw.y = pk2(st[8 * s2 + 2], st[8 * s2 + 3]); pw.z = pk2(st[8 * s2 + 4], st[8 * s2 + 5]); pw.w = pk2(st[8 * s2 + 6], st[8 * s2 + 7]);
;                 const bf16x8 pf = __builtin_bit_cast(bf16x8, pw);
;                 LAS const unsigned char* vp = lds + LDS_VOFF + (32 * wave + 32 * j + 16 * s2 + 4 * h + q) * VP + 32 * blk + 8 * p;
; #pragma unroll
;                 for (int dt = 0; dt < 2; ++dt) { const s16x4 lo = trrd(vp + dt * 64), hi = trrd(vp + 8 * VP + dt * 64);
;                     const bf16x8 vf = __builtin_shufflevector(lo, hi, 0, 1, 2, 3, 4, 5, 6, 7);
.LBB0_404:
	v_mov_b32_e32 v28, v177
	ds_read_b128 v[24:27], v206 offset:32
	s_and_b32 s65, s6, 7
	ds_read_b128 v[20:23], v206
	s_ashr_i32 s7, s6, 2
	s_add_i32 s6, s65, 1
	s_and_b32 s7, s7, -2
	s_lshr_b32 s8, 32, s7
	s_add_i32 s8, s8, -1
	s_and_b32 s8, s46, s8
	s_waitcnt vmcnt(0)
.Lattn2_join:
	v_xor_b32_e32 v32, 0x80000000, v229
	v_mov_b32_e32 v33, v32
	v_mov_b32_e32 v34, v32
	v_mov_b32_e32 v35, v32
	v_mov_b32_e32 v36, v32
	v_mov_b32_e32 v37, v32
	v_mov_b32_e32 v38, v32
	v_mov_b32_e32 v39, v32
	v_mov_b32_e32 v40, v32
	v_mov_b32_e32 v41, v32
	v_mov_b32_e32 v42, v32
	v_mov_b32_e32 v43, v32
	v_mov_b32_e32 v44, v32
	v_mov_b32_e32 v45, v32
	v_mov_b32_e32 v46, v32
	v_mov_b32_e32 v47, v32
	s_and_b32 s8, s8, 31
	s_waitcnt lgkmcnt(0)
	v_mfma_f32_32x32x16_bf16 v[0:15], v[20:23], v[136:139], v[32:47]
	ds_read_b128 v[20:23], v206 offset:64
	v_cvt_f32_ubyte0_e32 v16, s6
	v_exp_f32_e64 v29, -v16
	v_mfma_f32_32x32x16_bf16 v[0:15], v[24:27], v[132:135], v[0:15]
	s_lshl_b32 s66, s8, 8
	ds_read_b128 v[16:19], v206 offset:96
	s_add_i32 s66, s66, s48
	s_lshl_b32 s9, 1, s7
	s_lshr_b32 s7, 0x2000, s7
	s_waitcnt lgkmcnt(1)
	v_mfma_f32_32x32x16_bf16 v[0:15], v[20:23], v[128:131], v[0:15]
	v_or_b32_e32 v62, s66, v145
	v_sub_u32_e32 v20, 0, v62
	v_xad_u32 v21, v62, -1, s7
	v_cvt_f32_u32_e32 v24, s9
	v_cvt_f32_i32_e32 v171, v28
	v_max_i32_e32 v20, 0xffffffc0, v20
	v_min_i32_e32 v21, 64, v21
	s_waitcnt lgkmcnt(0)
	v_mfma_f32_32x32x16_bf16 v[0:15], v[16:19], v[140:143], v[0:15]
	v_cvt_f32_i32_e32 v168, v20
	v_cvt_f32_i32_e32 v169, v21
	v_mul_f32_e32 v24, v29, v24
	v_add_f32_e32 v16, 0xc2800000, v171
	v_mul_f32_e32 v170, 0xbfb8aa3b, v24
	v_cmp_nge_f32_e32 vcc, v16, v168
	v_cmp_nle_f32_e64 s[6:7], v16, v169
	s_nop 4
	v_fma_f32 v0, v170, |v16|, v0
	s_or_b64 vcc, vcc, s[6:7]
	v_add_f32_e32 v17, 0xc27c0000, v171
	v_cndmask_b32_e32 v0, v0, v228, vcc
	v_cmp_nge_f32_e32 vcc, v17, v168
	v_cmp_nle_f32_e64 s[6:7], v17, v169
	v_fma_f32 v1, v170, |v17|, v1
	s_or_b64 vcc, vcc, s[6:7]
	v_cndmask_b32_e32 v1, v1, v228, vcc
	v_exp_f32_e32 v17, v1
	v_add_f32_e32 v1, 0xc2780000, v171
	v_cmp_nge_f32_e32 vcc, v1, v168
	v_cmp_nle_f32_e64 s[6:7], v1, v169
	v_fma_f32 v2, v170, |v1|, v2
	s_or_b64 vcc, vcc, s[6:7]
	v_cndmask_b32_e32 v1, v2, v228, vcc
	v_exp_f32_e32 v18, v1
	v_add_f32_e32 v1, 0xc2740000, v171
	v_cmp_nge_f32_e32 vcc, v1, v168
	v_cmp_nle_f32_e64 s[6:7], v1, v169
	v_fma_f32 v2, v170, |v1|, v3
	s_or_b64 vcc, vcc, s[6:7]
	v_cndmask_b32_e32 v1, v2, v228, vcc
	v_exp_f32_e32 v19, v1
	v_add_f32_e32 v1, 0xc2600000, v171
	v_cmp_nge_f32_e32 vcc, v1, v168
	v_cmp_nle_f32_e64 s[6:7], v1, v169
	v_fma_f32 v2, v170, |v1|, v4
	s_or_b64 vcc, vcc, s[6:7]
	v_cndmask_b32_e32 v1, v2, v228, vcc
	v_exp_f32_e32 v20, v1
	v_add_f32_e32 v1, 0xc25c0000, v171
	v_cmp_nge_f32_e32 vcc, v1, v168
	v_cmp_nle_f32_e64 s[6:7], v1, v169
	v_fma_f32 v2, v170, |v1|, v5
	s_or_b64 vcc, vcc, s[6:7]
	v_cndmask_b32_e32 v1, v2, v228, vcc
	v_exp_f32_e32 v21, v1
	v_add_f32_e32 v1, 0xc2580000, v171
	v_cmp_nge_f32_e32 vcc, v1, v168
	v_cmp_nle_f32_e64 s[6:7], v1, v169
	v_fma_f32 v2, v170, |v1|, v6
	s_or_b64 vcc, vcc, s[6:7]
	v_cndmask_b32_e32 v1, v2, v228, vcc
	v_exp_f32_e32 v16, v0
	v_exp_f32_e32 v22, v1
	v_add_f32_e32 v1, 0xc2540000, v171
	v_cmp_nge_f32_e32 vcc, v1, v168
	v_cmp_nle_f32_e64 s[6:7], v1, v169
	v_fma_f32 v2, v170, |v1|, v7
	s_or_b64 vcc, vcc, s[6:7]
	v_cndmask_b32_e32 v1, v2, v228, vcc
	v_add_f32_e32 v0, 0, v16
	v_exp_f32_e32 v7, v1
	v_add_f32_e32 v1, 0xc2400000, v171
	v_add_f32_e32 v0, v17, v0
	v_cmp_nge_f32_e32 vcc, v1, v168
	v_cmp_nle_f32_e64 s[6:7], v1, v169
	v_add_f32_e32 v0, v18, v0
	v_fma_f32 v2, v170, |v1|, v8
	s_or_b64 vcc, vcc, s[6:7]
	v_add_f32_e32 v0, v19, v0
	v_cndmask_b32_e32 v1, v2, v228, vcc
	v_add_f32_e32 v0, v20, v0
	v_exp_f32_e32 v52, v1
	v_add_f32_e32 v0, v21, v0
	v_add_f32_e32 v0, v22, v0
	v_add_f32_e32 v0, v7, v0
	v_add_f32_e32 v60, v52, v0
	v_add_f32_e32 v0, 0xc23c0000, v171
	v_cmp_nge_f32_e32 vcc, v0, v168
	v_cmp_nle_f32_e64 s[6:7], v0, v169
	v_fma_f32 v1, v170, |v0|, v9
	s_or_b64 vcc, vcc, s[6:7]
	v_cndmask_b32_e32 v0, v1, v228, vcc
	v_exp_f32_e32 v61, v0
	v_add_f32_e32 v0, 0xc2380000, v171
	v_cmp_nge_f32_e32 vcc, v0, v168
	v_cmp_nle_f32_e64 s[6:7], v0, v169
	v_fma_f32 v1, v170, |v0|, v10
	s_or_b64 vcc, vcc, s[6:7]
	v_cndmask_b32_e32 v0, v1, v228, vcc
	v_exp_f32_e32 v62, v0
	v_add_f32_e32 v0, 0xc2340000, v171
	v_cmp_nge_f32_e32 vcc, v0, v168
	v_cmp_nle_f32_e64 s[6:7], v0, v169
	v_fma_f32 v1, v170, |v0|, v11
	s_or_b64 vcc, vcc, s[6:7]
	v_cndmask_b32_e32 v0, v1, v228, vcc
	v_exp_f32_e32 v63, v0
	v_add_f32_e32 v0, 0xc2200000, v171
	v_cmp_nge_f32_e32 vcc, v0, v168
	v_cmp_nle_f32_e64 s[6:7], v0, v169
	v_fma_f32 v1, v170, |v0|, v12
	s_or_b64 vcc, vcc, s[6:7]
	v_cndmask_b32_e32 v0, v1, v228, vcc
	v_exp_f32_e32 v172, v0
	v_add_f32_e32 v0, 0xc21c0000, v171
	v_cmp_nge_f32_e32 vcc, v0, v168
	v_cmp_nle_f32_e64 s[6:7], v0, v169
	v_fma_f32 v1, v170, |v0|, v13
	s_or_b64 vcc, vcc, s[6:7]
	v_cndmask_b32_e32 v0, v1, v228, vcc
	v_exp_f32_e32 v173, v0
	v_add_f32_e32 v0, 0xc2180000, v171
	v_cmp_nge_f32_e32 vcc, v0, v168
	v_cmp_nle_f32_e64 s[6:7], v0, v169
	v_fma_f32 v1, v170, |v0|, v14
	s_or_b64 vcc, vcc, s[6:7]
	v_cndmask_b32_e32 v4, v1, v228, vcc
	ds_read_b64_tr_b16 v[0:1], v207 offset:55296
	ds_read_b64_tr_b16 v[2:3], v207 offset:56832
	ds_read_b64_tr_b16 v[10:11], v207 offset:56896
	ds_read_b64_tr_b16 v[8:9], v207 offset:55360
	v_add_f32_e32 v12, 0xc2140000, v171
	v_exp_f32_e32 v174, v4
	v_cvt_pk_bf16_f32 v4, v16, v17
	v_cvt_pk_bf16_f32 v5, v18, v19
	v_cvt_pk_bf16_f32 v6, v20, v21
	v_cvt_pk_bf16_f32 v7, v22, v7
	v_cmp_nge_f32_e32 vcc, v12, v168
	v_cmp_nle_f32_e64 s[6:7], v12, v169
	s_waitcnt lgkmcnt(2)
	v_mfma_f32_32x32x16_bf16 v[16:31], v[0:3], v[4:7], 0
	v_fma_f32 v0, v170, |v12|, v15
	s_or_b64 vcc, vcc, s[6:7]
	v_cndmask_b32_e32 v53, v0, v228, vcc
	ds_read_b64_tr_b16 v[48:49], v207 offset:58368
	ds_read_b64_tr_b16 v[50:51], v207 offset:59904
	v_exp_f32_e32 v175, v53
	ds_read_b64_tr_b16 v[58:59], v207 offset:59968
	ds_read_b64_tr_b16 v[56:57], v207 offset:58432
	v_cvt_pk_bf16_f32 v52, v52, v61
	s_waitcnt lgkmcnt(4)
	v_mfma_f32_32x32x16_bf16 v[0:15], v[8:11], v[4:7], 0
	v_cvt_pk_bf16_f32 v53, v62, v63
	v_cvt_pk_bf16_f32 v54, v172, v173
	v_cvt_pk_bf16_f32 v55, v174, v175
	s_waitcnt lgkmcnt(2)
	s_nop 0
	v_mfma_f32_32x32x16_bf16 v[16:31], v[48:51], v[52:55], v[16:31]
	v_add_f32_e32 v48, v61, v60
	v_add_f32_e32 v48, v62, v48
	v_add_f32_e32 v48, v63, v48
	v_add_f32_e32 v48, v172, v48
	v_add_f32_e32 v48, v173, v48
	v_add_f32_e32 v48, v174, v48
	v_add_f32_e32 v48, v175, v48
	s_waitcnt lgkmcnt(0)
	v_mfma_f32_32x32x16_bf16 v[0:15], v[56:59], v[52:55], v[0:15]
	v_add_f32_e32 v238, 0, v48
	v_cmp_neq_f32_e32 vcc, 0xc2800000, v168
	s_mov_b64 s[6:7], vcc
	v_cmp_neq_f32_e32 vcc, 0x42800000, v169
	s_or_b64 vcc, vcc, s[6:7]
	s_cbranch_vccnz .Lattn2_slow
; #define LAS __attribute__((address_space(3)))
; __device__ __forceinline__ unsigned pk2(float lo, float hi) { f32x2_t v = {lo, hi}; bf16x2_t b = __builtin_convertvector(v, bf16x2_t); return __builtin_bit_cast(unsigned, b); }
; __device__ __forceinline__ s16x4 trrd(LAS const unsigned char* p) { return __builtin_bit_cast(s16x4, __builtin_amdgcn_ds_read_tr16_b64_v4i16((LAS v4i16_t*)p)); }
; __device__ __forceinline__ float attn_tile_exp(f32x16& st, int j, float tlf, float bsl, float rlo, float rhi) {
;     float sum = 0.f;
; #pragma unroll
;     for (int i = 0; i < 16; ++i) { const float tmp = (float)(32 * j - 64 + (i & 3) + 8 * (i >> 2)) + tlf;
;         float arg = __builtin_fmaf(-bsl, __builtin_fabsf(tmp), st[i]);
;         arg = (tmp >= rlo && tmp <= rhi) ? arg : -1.0e30f;
;         const float pe = __builtin_amdgcn_exp2f(arg); st[i] = pe; sum += pe; }
;     return sum;
; }
; template <bool FUSED> __device__ __forceinline__ void attn_phase(const Args& a, LAS unsigned char* lds, int tid, int lane, int wave) {
;     ...
; #pragma unroll
;         for (int j = 0; j < 5; ++j) {
;             f32x16 st;
; #pragma unroll
;             for (int i = 0; i < 16; ++i) st[i] = -mb;
;             LAS const unsigned char* kp = lds + (32 * wave + 32 * j + l31) * KP + 16 * h;
; #pragma unroll
;             for (int ks = 0; ks < 4; ++ks) { const bf16x8 kf = *(LAS const bf16x8*)(kp + 32 * ks); st = __builtin_amdgcn_mfma_f32_32x32x16_bf16(kf, qf[ks], st, 0, 0, 0); }
;             sum += attn_tile_exp(st, j, tlf, bsl, rlo, rhi);
; #pragma unroll
;             for (int s2 = 0; s2 < 2; ++s2) { u32x4 pw; pw.x = pk2(st[8 * s2 + 0], st[8 * s2 + 1]); pw.y = pk2(st[8 * s2 + 2], st[8 * s2 + 3]); pw.z = pk2(st[8 * s2 + 4], st[8 * s2 + 5]); pw.w = pk2(st[8 * s2 + 6], st[8 * s2 + 7]);
;                 const bf16x8 pf = __builtin_bit_cast(bf16x8, pw);
;                 LAS const unsigned char* vp = lds + LDS_VOFF + (32 * wave + 32 * j + 16 * s2 + 4 * h + q) * VP + 32 * blk + 8 * p;
; #pragma unroll
;                 for (int dt = 0; dt < 2; ++dt) { const s16x4 lo = trrd(vp + dt * 64), hi = trrd(vp + 8 * VP + dt * 64);
;                     const bf16x8 vf = __builtin_shufflevector(lo, hi, 0, 1, 2, 3, 4, 5, 6, 7);
;                     o[dt] = __builtin_amdgcn_mfma_f32_32x32x16_bf16(vf, pf, o[dt], 0, 0, 0); } }
	ds_read_b128 v[172:175], v208
	ds_read_b128 v[230:233], v208 offset:32
	v_add_f32_e32 v239, 0xc2000000, v171
	v_add_f32_e32 v240, 0xc1f80000, v171
	s_waitcnt lgkmcnt(1)
	v_mfma_f32_32x32x16_bf16 v[48:63], v[172:175], v[136:139], v[32:47]
	ds_read_b128 v[172:175], v208 offset:64
	ds_read_b128 v[234:237], v208 offset:96
	v_add_f32_e32 v241, 0xc1f00000, v171
	v_add_f32_e32 v242, 0xc1e80000, v171
	s_waitcnt lgkmcnt(2)
	v_mfma_f32_32x32x16_bf16 v[48:63], v[230:233], v[132:135], v[48:63]
	v_add_f32_e32 v230, 0xc1c00000, v171
	v_add_f32_e32 v231, 0xc1b80000, v171
	s_waitcnt lgkmcnt(1)
	v_mfma_f32_32x32x16_bf16 v[48:63], v[172:175], v[128:131], v[48:63]
	s_waitcnt lgkmcnt(0)
	v_mfma_f32_32x32x16_bf16 v[48:63], v[234:237], v[140:143], v[48:63]
	s_nop 11
	v_fma_f32 v48, v170, |v239|, v48
	v_fma_f32 v49, v170, |v240|, v49
	v_fma_f32 v50, v170, |v241|, v50
	v_fma_f32 v51, v170, |v242|, v51
	v_fma_f32 v52, v170, |v230|, v52
	v_fma_f32 v53, v170, |v231|, v53
	v_exp_f32_e32 v173, v49
	v_mov_b32_e32 v49, v53
	v_exp_f32_e32 v231, v49
	v_add_f32_e32 v49, 0xc1b00000, v171
	v_exp_f32_e32 v174, v50
	v_fma_f32 v49, v170, |v49|, v54
	v_exp_f32_e32 v172, v48
	v_exp_f32_e32 v232, v49
	v_add_f32_e32 v49, 0xc1a80000, v171
	v_fma_f32 v49, v170, |v49|, v55
	v_exp_f32_e32 v175, v51
	v_exp_f32_e32 v230, v52
	v_add_f32_e32 v48, 0, v172
	v_exp_f32_e32 v55, v49
	v_add_f32_e32 v49, 0xc1800000, v171
	v_add_f32_e32 v48, v173, v48
	v_add_f32_e32 v48, v174, v48
	v_fma_f32 v49, v170, |v49|, v56
	v_add_f32_e32 v48, v175, v48
	v_add_f32_e32 v48, v230, v48
	v_exp_f32_e32 v233, v49
	v_add_f32_e32 v48, v231, v48
	v_add_f32_e32 v48, v232, v48
	v_add_f32_e32 v48, v55, v48
	v_add_f32_e32 v234, v233, v48
	v_add_f32_e32 v48, 0xc1700000, v171
	v_fma_f32 v48, v170, |v48|, v57
	v_exp_f32_e32 v235, v48
	v_add_f32_e32 v48, 0xc1600000, v171
	v_fma_f32 v48, v170, |v48|, v58
	v_exp_f32_e32 v236, v48
	v_add_f32_e32 v48, 0xc1500000, v171
	v_fma_f32 v48, v170, |v48|, v59
	v_exp_f32_e32 v237, v48
	v_add_f32_e32 v48, 0xc1000000, v171
	v_fma_f32 v48, v170, |v48|, v60
	v_exp_f32_e32 v60, v48
	v_add_f32_e32 v48, 0xc0e00000, v171
	v_fma_f32 v48, v170, |v48|, v61
	v_exp_f32_e32 v61, v48
	v_add_f32_e32 v48, 0xc0c00000, v171
	v_fma_f32 v52, v170, |v48|, v62
	ds_read_b64_tr_b16 v[48:49], v209 offset:55296
	ds_read_b64_tr_b16 v[50:51], v209 offset:56832
	ds_read_b64_tr_b16 v[58:59], v209 offset:56896
	ds_read_b64_tr_b16 v[56:57], v209 offset:55360
	v_exp_f32_e32 v62, v52
	v_add_f32_e32 v239, 0xc0a00000, v171
	v_cvt_pk_bf16_f32 v52, v172, v173
	v_cvt_pk_bf16_f32 v53, v174, v175
	v_cvt_pk_bf16_f32 v54, v230, v231
	v_cvt_pk_bf16_f32 v55, v232, v55
	s_waitcnt lgkmcnt(2)
	s_nop 0
	v_mfma_f32_32x32x16_bf16 v[16:31], v[48:51], v[52:55], v[16:31]
	v_fma_f32 v63, v170, |v239|, v63
	ds_read_b64_tr_b16 v[48:49], v209 offset:58368
	ds_read_b64_tr_b16 v[50:51], v209 offset:59904
	v_exp_f32_e32 v63, v63
	s_waitcnt lgkmcnt(2)
	v_mfma_f32_32x32x16_bf16 v[0:15], v[56:59], v[52:55], v[0:15]
	ds_read_b64_tr_b16 v[58:59], v209 offset:59968
	ds_read_b64_tr_b16 v[56:57], v209 offset:58432
	v_cvt_pk_bf16_f32 v52, v233, v235
	v_cvt_pk_bf16_f32 v53, v236, v237
	v_cvt_pk_bf16_f32 v54, v60, v61
	v_cvt_pk_bf16_f32 v55, v62, v63
	s_waitcnt lgkmcnt(2)
	s_nop 0
	v_mfma_f32_32x32x16_bf16 v[16:31], v[48:51], v[52:55], v[16:31]
	v_add_f32_e32 v48, v235, v234
	v_add_f32_e32 v48, v236, v48
	v_add_f32_e32 v48, v237, v48
	v_add_f32_e32 v48, v60, v48
	v_add_f32_e32 v48, v61, v48
	v_add_f32_e32 v48, v62, v48
	v_add_f32_e32 v48, v63, v48
	s_waitcnt lgkmcnt(0)
	v_mfma_f32_32x32x16_bf16 v[0:15], v[56:59], v[52:55], v[0:15]
	v_add_f32_e32 v238, v238, v48
	ds_read_b128 v[172:175], v210
	ds_read_b128 v[230:233], v210 offset:32
	v_add_f32_e32 v239, 1.0, v171
	s_waitcnt lgkmcnt(1)
	v_mfma_f32_32x32x16_bf16 v[48:63], v[172:175], v[136:139], v[32:47]
	ds_read_b128 v[172:175], v210 offset:64
	ds_read_b128 v[234:237], v210 offset:96
	s_waitcnt lgkmcnt(2)
	v_mfma_f32_32x32x16_bf16 v[48:63], v[230:233], v[132:135], v[48:63]
	v_add_f32_e32 v230, 2.0, v171
	v_add_f32_e32 v231, 0x40400000, v171
	v_add_f32_e32 v232, 0x41000000, v171
	s_waitcnt lgkmcnt(1)
	v_mfma_f32_32x32x16_bf16 v[48:63], v[172:175], v[128:131], v[48:63]
	v_add_f32_e32 v233, 0x41100000, v171
	s_waitcnt lgkmcnt(0)
	v_mfma_f32_32x32x16_bf16 v[48:63], v[234:237], v[140:143], v[48:63]
	s_nop 11
	v_fma_f32 v48, v170, |v171|, v48
	v_fma_f32 v49, v170, |v239|, v49
	v_fma_f32 v50, v170, |v230|, v50
	v_fma_f32 v51, v170, |v231|, v51
	v_fma_f32 v52, v170, |v232|, v52
	v_fma_f32 v53, v170, |v233|, v53
	v_exp_f32_e32 v173, v49
	v_mov_b32_e32 v49, v53
	v_exp_f32_e32 v231, v49
	v_add_f32_e32 v49, 0x41200000, v171
	v_exp_f32_e32 v174, v50
	v_fma_f32 v49, v170, |v49|, v54
	v_exp_f32_e32 v172, v48
	v_exp_f32_e32 v232, v49
	v_add_f32_e32 v49, 0x41300000, v171
	v_fma_f32 v49, v170, |v49|, v55
	v_exp_f32_e32 v175, v51
	v_exp_f32_e32 v230, v52
	v_add_f32_e32 v48, 0, v172
	v_exp_f32_e32 v55, v49
	v_add_f32_e32 v49, 0x41800000, v171
	v_add_f32_e32 v48, v173, v48
	v_add_f32_e32 v48, v174, v48
	v_fma_f32 v49, v170, |v49|, v56
	v_add_f32_e32 v48, v175, v48
	v_add_f32_e32 v48, v230, v48
	v_exp_f32_e32 v233, v49
	v_add_f32_e32 v48, v231, v48
	v_add_f32_e32 v48, v232, v48
	v_add_f32_e32 v48, v55, v48
	v_add_f32_e32 v234, v233, v48
	v_add_f32_e32 v48, 0x41880000, v171
	v_fma_f32 v48, v170, |v48|, v57
	v_exp_f32_e32 v235, v48
	v_add_f32_e32 v48, 0x41900000, v171
	v_fma_f32 v48, v170, |v48|, v58
	v_exp_f32_e32 v236, v48
	v_add_f32_e32 v48, 0x41980000, v171
	v_fma_f32 v48, v170, |v48|, v59
	v_exp_f32_e32 v237, v48
	v_add_f32_e32 v48, 0x41c00000, v171
	v_fma_f32 v48, v170, |v48|, v60
	v_exp_f32_e32 v60, v48
	v_add_f32_e32 v48, 0x41c80000, v171
	v_fma_f32 v48, v170, |v48|, v61
	v_exp_f32_e32 v61, v48
	v_add_f32_e32 v48, 0x41d00000, v171
	v_fma_f32 v52, v170, |v48|, v62
	ds_read_b64_tr_b16 v[48:49], v211 offset:55296
	ds_read_b64_tr_b16 v[50:51], v211 offset:56832
	ds_read_b64_tr_b16 v[58:59], v211 offset:56896
	ds_read_b64_tr_b16 v[56:57], v211 offset:55360
	v_exp_f32_e32 v62, v52
	v_add_f32_e32 v239, 0x41d80000, v171
	v_cvt_pk_bf16_f32 v52, v172, v173
	v_cvt_pk_bf16_f32 v53, v174, v175
	v_cvt_pk_bf16_f32 v54, v230, v231
	v_cvt_pk_bf16_f32 v55, v232, v55
	s_waitcnt lgkmcnt(2)
; #define LAS __attribute__((address_space(3)))
; __device__ __forceinline__ unsigned pk2(float lo, float hi) { f32x2_t v = {lo, hi}; bf16x2_t b = __builtin_convertvector(v, bf16x2_t); return __builtin_bit_cast(unsigned, b); }
; __device__ __forceinline__ s16x4 trrd(LAS const unsigned char* p) { return __builtin_bit_cast(s16x4, __builtin_amdgcn_ds_read_tr16_b64_v4i16((LAS v4i16_t*)p)); }
; __device__ __forceinline__ float attn_tile_exp(f32x16& st, int j, float tlf, float bsl, float rlo, float rhi) {
;     float sum = 0.f;
; #pragma unroll
;     for (int i = 0; i < 16; ++i) { const float tmp = (float)(32 * j - 64 + (i & 3) + 8 * (i >> 2)) + tlf;
;         float arg = __builtin_fmaf(-bsl, __builtin_fabsf(tmp), st[i]);
;         arg = (tmp >= rlo && tmp <= rhi) ? arg : -1.0e30f;
;         const float pe = __builtin_amdgcn_exp2f(arg); st[i] = pe; sum += pe; }
;     return sum;
; }
; template <bool FUSED> __device__ __forceinline__ void attn_phase(const Args& a, LAS unsigned char* lds, int tid, int lane, int wave) {
;     ...
; #pragma unroll
;         for (int j = 0; j < 5; ++j) {
;             f32x16 st;
; #pragma unroll
;             for (int i = 0; i < 16; ++i) st[i] = -mb;
;             LAS const unsigned char* kp = lds + (32 * wave + 32 * j + l31) * KP + 16 * h;
; #pragma unroll
;             for (int ks = 0; ks < 4; ++ks) { const bf16x8 kf = *(LAS const bf16x8*)(kp + 32 * ks); st = __builtin_amdgcn_mfma_f32_32x32x16_bf16(kf, qf[ks], st, 0, 0, 0); }
;             sum += attn_tile_exp(st, j, tlf, bsl, rlo, rhi);
; #pragma unroll
;             for (int s2 = 0; s2 < 2; ++s2) { u32x4 pw; pw.x = pk2(st[8 * s2 + 0], st[8 * s2 + 1]); pw.y = pk2(st[8 * s2 + 2], st[8 * s2 + 3]); pw.z = pk2(st[8 * s2 + 4], st[8 * s2 + 5]); pw.w = pk2(st[8 * s2 + 6], st[8 * s2 + 7]);
;                 const bf16x8 pf = __builtin_bit_cast(bf16x8, pw);
;                 LAS const unsigned char* vp = lds + LDS_VOFF + (32 * wave + 32 * j + 16 * s2 + 4 * h + q) * VP + 32 * blk + 8 * p;
; #pragma unroll
;                 for (int dt = 0; dt < 2; ++dt) { const s16x4 lo = trrd(vp + dt * 64), hi = trrd(vp + 8 * VP + dt * 64);
;                     const bf16x8 vf = __builtin_shufflevector(lo, hi, 0, 1, 2, 3, 4, 5, 6, 7);
;                     o[dt] = __builtin_amdgcn_mfma_f32_32x32x16_bf16(vf, pf, o[dt], 0, 0, 0); } }
;             __builtin_amdgcn_sched_barrier(0);
;         }
	s_nop 0
	v_mfma_f32_32x32x16_bf16 v[16:31], v[48:51], v[52:55], v[16:31]
	v_fma_f32 v63, v170, |v239|, v63
	ds_read_b64_tr_b16 v[48:49], v211 offset:58368
	ds_read_b64_tr_b16 v[50:51], v211 offset:59904
	v_exp_f32_e32 v63, v63
	s_waitcnt lgkmcnt(2)
	v_mfma_f32_32x32x16_bf16 v[0:15], v[56:59], v[52:55], v[0:15]
	ds_read_b64_tr_b16 v[58:59], v211 offset:59968
	ds_read_b64_tr_b16 v[56:57], v211 offset:58432
	v_cvt_pk_bf16_f32 v52, v233, v235
	v_cvt_pk_bf16_f32 v53, v236, v237
	v_cvt_pk_bf16_f32 v54, v60, v61
	v_cvt_pk_bf16_f32 v55, v62, v63
	s_waitcnt lgkmcnt(2)
	s_nop 0
	v_mfma_f32_32x32x16_bf16 v[16:31], v[48:51], v[52:55], v[16:31]
	v_add_f32_e32 v48, v235, v234
	v_add_f32_e32 v48, v236, v48
	v_add_f32_e32 v48, v237, v48
	v_add_f32_e32 v48, v60, v48
	v_add_f32_e32 v48, v61, v48
	v_add_f32_e32 v48, v62, v48
	v_add_f32_e32 v48, v63, v48
	s_waitcnt lgkmcnt(0)
	v_mfma_f32_32x32x16_bf16 v[0:15], v[56:59], v[52:55], v[0:15]
	v_add_f32_e32 v238, v238, v48
	ds_read_b128 v[172:175], v212
	ds_read_b128 v[230:233], v212 offset:32
	v_add_f32_e32 v239, 0x42000000, v171
	v_add_f32_e32 v240, 0x42040000, v171
	s_waitcnt lgkmcnt(1)
	v_mfma_f32_32x32x16_bf16 v[48:63], v[172:175], v[136:139], v[32:47]
	ds_read_b128 v[172:175], v212 offset:64
	ds_read_b128 v[234:237], v212 offset:96
	v_add_f32_e32 v241, 0x42080000, v171
	v_add_f32_e32 v242, 0x420c0000, v171
	s_waitcnt lgkmcnt(2)
	v_mfma_f32_32x32x16_bf16 v[48:63], v[230:233], v[132:135], v[48:63]
	v_add_f32_e32 v230, 0x42200000, v171
	v_add_f32_e32 v231, 0x42240000, v171
	s_waitcnt lgkmcnt(1)
	v_mfma_f32_32x32x16_bf16 v[48:63], v[172:175], v[128:131], v[48:63]
	s_waitcnt lgkmcnt(0)
	v_mfma_f32_32x32x16_bf16 v[48:63], v[234:237], v[140:143], v[48:63]
	s_nop 11
	v_fma_f32 v48, v170, |v239|, v48
	v_fma_f32 v49, v170, |v240|, v49
	v_fma_f32 v50, v170, |v241|, v50
	v_fma_f32 v51, v170, |v242|, v51
	v_fma_f32 v52, v170, |v230|, v52
	v_fma_f32 v53, v170, |v231|, v53
	v_exp_f32_e32 v173, v49
	v_mov_b32_e32 v49, v53
	v_exp_f32_e32 v231, v49
	v_add_f32_e32 v49, 0x42280000, v171
	v_exp_f32_e32 v174, v50
	v_fma_f32 v49, v170, |v49|, v54
	v_exp_f32_e32 v172, v48
	v_exp_f32_e32 v232, v49
	v_add_f32_e32 v49, 0x422c0000, v171
	v_fma_f32 v49, v170, |v49|, v55
	v_exp_f32_e32 v175, v51
	v_exp_f32_e32 v230, v52
	v_add_f32_e32 v48, 0, v172
	v_exp_f32_e32 v55, v49
	v_add_f32_e32 v49, 0x42400000, v171
	v_add_f32_e32 v48, v173, v48
	v_add_f32_e32 v48, v174, v48
	v_fma_f32 v49, v170, |v49|, v56
	v_add_f32_e32 v48, v175, v48
	v_add_f32_e32 v48, v230, v48
	v_exp_f32_e32 v233, v49
	v_add_f32_e32 v48, v231, v48
	v_add_f32_e32 v48, v232, v48
	v_add_f32_e32 v48, v55, v48
	v_add_f32_e32 v234, v233, v48
	v_add_f32_e32 v48, 0x42440000, v171
	v_fma_f32 v48, v170, |v48|, v57
	v_exp_f32_e32 v235, v48
	v_add_f32_e32 v48, 0x42480000, v171
	v_fma_f32 v48, v170, |v48|, v58
	v_exp_f32_e32 v236, v48
	v_add_f32_e32 v48, 0x424c0000, v171
	v_fma_f32 v48, v170, |v48|, v59
	v_exp_f32_e32 v237, v48
	v_add_f32_e32 v48, 0x42600000, v171
	v_fma_f32 v48, v170, |v48|, v60
	v_exp_f32_e32 v60, v48
	v_add_f32_e32 v48, 0x42640000, v171
	v_fma_f32 v48, v170, |v48|, v61
	v_exp_f32_e32 v61, v48
	v_add_f32_e32 v48, 0x42680000, v171
	v_fma_f32 v52, v170, |v48|, v62
	ds_read_b64_tr_b16 v[48:49], v213 offset:55296
	ds_read_b64_tr_b16 v[50:51], v213 offset:56832
	ds_read_b64_tr_b16 v[58:59], v213 offset:56896
	ds_read_b64_tr_b16 v[56:57], v213 offset:55360
	v_exp_f32_e32 v62, v52
	v_add_f32_e32 v239, 0x426c0000, v171
	v_cvt_pk_bf16_f32 v52, v172, v173
	v_cvt_pk_bf16_f32 v53, v174, v175
	v_cvt_pk_bf16_f32 v54, v230, v231
	v_cvt_pk_bf16_f32 v55, v232, v55
	s_waitcnt lgkmcnt(2)
	s_nop 0
	v_mfma_f32_32x32x16_bf16 v[16:31], v[48:51], v[52:55], v[16:31]
	v_fma_f32 v63, v170, |v239|, v63
	ds_read_b64_tr_b16 v[48:49], v213 offset:58368
	ds_read_b64_tr_b16 v[50:51], v213 offset:59904
	v_exp_f32_e32 v63, v63
	s_waitcnt lgkmcnt(2)
	v_mfma_f32_32x32x16_bf16 v[0:15], v[56:59], v[52:55], v[0:15]
	ds_read_b64_tr_b16 v[58:59], v213 offset:59968
	ds_read_b64_tr_b16 v[56:57], v213 offset:58432
	v_cvt_pk_bf16_f32 v52, v233, v235
	v_cvt_pk_bf16_f32 v53, v236, v237
	v_cvt_pk_bf16_f32 v54, v60, v61
	v_cvt_pk_bf16_f32 v55, v62, v63
	s_waitcnt lgkmcnt(2)
	s_nop 0
	v_mfma_f32_32x32x16_bf16 v[16:31], v[48:51], v[52:55], v[16:31]
	v_add_f32_e32 v48, v235, v234
	v_add_f32_e32 v48, v236, v48
	v_add_f32_e32 v48, v237, v48
	v_add_f32_e32 v48, v60, v48
	v_add_f32_e32 v48, v61, v48
	v_add_f32_e32 v48, v62, v48
	v_add_f32_e32 v48, v63, v48
	s_waitcnt lgkmcnt(0)
	v_mfma_f32_32x32x16_bf16 v[0:15], v[56:59], v[52:55], v[0:15]
	v_add_f32_e32 v60, v238, v48
	s_branch .Lattn2_t4
